# q64 attention: V fragments read straight into MFMA operand registers (no v_mov shuffles), on top of up tile remap
# speedup vs baseline: 1.0117x; 1.0035x over previous
; DI float ex2(float x) { return __builtin_amdgcn_exp2f(x); }
; DI void attn_item_q64(const AttnArgs& a, char* smem) {
;     ...
; #pragma unroll
;       for (int kb = 0; kb < 2; ++kb)
; #pragma unroll
;         for (int i = 0; i < 16; i += 2) {
;           f32x2n v = {s[q2][kb][i], s[q2][kb][i + 1]};
;           v = v * f32x2n{SC, SC} - f32x2n{mn, mn};
;           const float p0 = ex2(v.x), p1 = ex2(v.y);
;           s[q2][kb][i] = p0; s[q2][kb][i + 1] = p1;
;           ps0 += p0; ps1 += p1;
;     ...
; #pragma unroll
;         for (int d = 0; d < 2; ++d) {
;           const char* vrow = Vs + (d * 32 + r) * 128 + 8 * h;
;           u32x4 vv;
;           const u32x2 lo = *(const u32x2*)(vrow + (((2 * kk) ^ sw) << 4));
;           const u32x2 hi = *(const u32x2*)(vrow + (((2 * kk + 1) ^ sw) << 4));
;           vv.x = lo.x; vv.y = lo.y; vv.z = hi.x; vv.w = hi.y;
;           const bf8 vf = __builtin_bit_cast(bf8, vv);
.LBB0_427:
	v_pk_fma_f32 v[128:129], v[128:129], s[24:25], v[0:1] op_sel_hi:[1,0,0] neg_lo:[0,0,1] neg_hi:[0,0,1]
	v_pk_fma_f32 v[98:99], v[98:99], s[24:25], v[0:1] op_sel_hi:[1,0,0] neg_lo:[0,0,1] neg_hi:[0,0,1]
	v_pk_fma_f32 v[100:101], v[100:101], s[24:25], v[0:1] op_sel_hi:[1,0,0] neg_lo:[0,0,1] neg_hi:[0,0,1]
	v_pk_fma_f32 v[102:103], v[102:103], s[24:25], v[0:1] op_sel_hi:[1,0,0] neg_lo:[0,0,1] neg_hi:[0,0,1]
	v_pk_fma_f32 v[104:105], v[104:105], s[24:25], v[0:1] op_sel_hi:[1,0,0] neg_lo:[0,0,1] neg_hi:[0,0,1]
	v_pk_fma_f32 v[106:107], v[106:107], s[24:25], v[0:1] op_sel_hi:[1,0,0] neg_lo:[0,0,1] neg_hi:[0,0,1]
	v_pk_fma_f32 v[108:109], v[108:109], s[24:25], v[0:1] op_sel_hi:[1,0,0] neg_lo:[0,0,1] neg_hi:[0,0,1]
	v_pk_fma_f32 v[110:111], v[110:111], s[24:25], v[0:1] op_sel_hi:[1,0,0] neg_lo:[0,0,1] neg_hi:[0,0,1]
	v_pk_fma_f32 v[112:113], v[112:113], s[24:25], v[0:1] op_sel_hi:[1,0,0] neg_lo:[0,0,1] neg_hi:[0,0,1]
	v_pk_fma_f32 v[114:115], v[114:115], s[24:25], v[0:1] op_sel_hi:[1,0,0] neg_lo:[0,0,1] neg_hi:[0,0,1]
	v_pk_fma_f32 v[116:117], v[116:117], s[24:25], v[0:1] op_sel_hi:[1,0,0] neg_lo:[0,0,1] neg_hi:[0,0,1]
	v_pk_fma_f32 v[118:119], v[118:119], s[24:25], v[0:1] op_sel_hi:[1,0,0] neg_lo:[0,0,1] neg_hi:[0,0,1]
	v_pk_fma_f32 v[120:121], v[120:121], s[24:25], v[0:1] op_sel_hi:[1,0,0] neg_lo:[0,0,1] neg_hi:[0,0,1]
	v_pk_fma_f32 v[122:123], v[122:123], s[24:25], v[0:1] op_sel_hi:[1,0,0] neg_lo:[0,0,1] neg_hi:[0,0,1]
	v_pk_fma_f32 v[124:125], v[124:125], s[24:25], v[0:1] op_sel_hi:[1,0,0] neg_lo:[0,0,1] neg_hi:[0,0,1]
	v_pk_fma_f32 v[126:127], v[126:127], s[24:25], v[0:1] op_sel_hi:[1,0,0] neg_lo:[0,0,1] neg_hi:[0,0,1]
	v_exp_f32_e32 v0, v128
	v_exp_f32_e32 v128, v129
	v_add_u32_e32 v129, s14, v180
	v_pk_fma_f32 v[66:67], v[66:67], s[24:25], v[172:173] op_sel_hi:[1,0,0] neg_lo:[0,0,1] neg_hi:[0,0,1]
	v_pk_fma_f32 v[68:69], v[68:69], s[24:25], v[172:173] op_sel_hi:[1,0,0] neg_lo:[0,0,1] neg_hi:[0,0,1]
	v_pk_fma_f32 v[70:71], v[70:71], s[24:25], v[172:173] op_sel_hi:[1,0,0] neg_lo:[0,0,1] neg_hi:[0,0,1]
	v_pk_fma_f32 v[72:73], v[72:73], s[24:25], v[172:173] op_sel_hi:[1,0,0] neg_lo:[0,0,1] neg_hi:[0,0,1]
	v_pk_fma_f32 v[74:75], v[74:75], s[24:25], v[172:173] op_sel_hi:[1,0,0] neg_lo:[0,0,1] neg_hi:[0,0,1]
	v_pk_fma_f32 v[76:77], v[76:77], s[24:25], v[172:173] op_sel_hi:[1,0,0] neg_lo:[0,0,1] neg_hi:[0,0,1]
	v_pk_fma_f32 v[78:79], v[78:79], s[24:25], v[172:173] op_sel_hi:[1,0,0] neg_lo:[0,0,1] neg_hi:[0,0,1]
	v_pk_fma_f32 v[80:81], v[80:81], s[24:25], v[172:173] op_sel_hi:[1,0,0] neg_lo:[0,0,1] neg_hi:[0,0,1]
	v_pk_fma_f32 v[82:83], v[82:83], s[24:25], v[172:173] op_sel_hi:[1,0,0] neg_lo:[0,0,1] neg_hi:[0,0,1]
	v_pk_fma_f32 v[84:85], v[84:85], s[24:25], v[172:173] op_sel_hi:[1,0,0] neg_lo:[0,0,1] neg_hi:[0,0,1]
	v_pk_fma_f32 v[86:87], v[86:87], s[24:25], v[172:173] op_sel_hi:[1,0,0] neg_lo:[0,0,1] neg_hi:[0,0,1]
	v_pk_fma_f32 v[88:89], v[88:89], s[24:25], v[172:173] op_sel_hi:[1,0,0] neg_lo:[0,0,1] neg_hi:[0,0,1]
	v_pk_fma_f32 v[90:91], v[90:91], s[24:25], v[172:173] op_sel_hi:[1,0,0] neg_lo:[0,0,1] neg_hi:[0,0,1]
	v_pk_fma_f32 v[92:93], v[92:93], s[24:25], v[172:173] op_sel_hi:[1,0,0] neg_lo:[0,0,1] neg_hi:[0,0,1]
	v_pk_fma_f32 v[94:95], v[94:95], s[24:25], v[172:173] op_sel_hi:[1,0,0] neg_lo:[0,0,1] neg_hi:[0,0,1]
	v_pk_fma_f32 v[96:97], v[96:97], s[24:25], v[172:173] op_sel_hi:[1,0,0] neg_lo:[0,0,1] neg_hi:[0,0,1]
	v_add_u32_e32 v172, v129, v181
	ds_read_b64 v[230:231], v172 offset:16384
	ds_read_b64 v[226:227], v172 offset:20480
	v_add_u32_e32 v172, v129, v182
	ds_read_b64 v[232:233], v172 offset:16384
	ds_read_b64 v[228:229], v172 offset:20480
	v_exp_f32_e32 v98, v98
	v_exp_f32_e32 v99, v99
	v_exp_f32_e32 v100, v100
	v_exp_f32_e32 v101, v101
	v_exp_f32_e32 v102, v102
	v_exp_f32_e32 v103, v103
	v_exp_f32_e32 v104, v104
	v_exp_f32_e32 v105, v105
	v_exp_f32_e32 v66, v66
	v_exp_f32_e32 v67, v67
	v_exp_f32_e32 v68, v68
	v_exp_f32_e32 v69, v69
	v_exp_f32_e32 v70, v70
	v_exp_f32_e32 v71, v71
	v_exp_f32_e32 v72, v72
	v_exp_f32_e32 v73, v73
	s_waitcnt lgkmcnt(0)
; DI unsigned pack2(float a, float b) { f2 v = {a, b}; bf2 r = __builtin_convertvector(v, bf2); return __builtin_bit_cast(unsigned, r); }
; DI f32x16 mfma32(bf8 a, bf8 b, f32x16 c) { return __builtin_amdgcn_mfma_f32_32x32x16_bf16(a, b, c, 0, 0, 0); }
; DI void attn_item_q64(const AttnArgs& a, char* smem) {
;     ...
; #pragma unroll
;     for (int kb = 0; kb < 2; ++kb)
; #pragma unroll
;       for (int s2 = 0; s2 < 2; ++s2) {
;         const int kk = kb * 2 + s2;
;         bf8 pf[2];
; #pragma unroll
;         for (int q2 = 0; q2 < 2; ++q2) {
;           u32x4 pk;
;           pk.x = pack2(s[q2][kb][s2 * 8 + 0], s[q2][kb][s2 * 8 + 1]);
;           pk.y = pack2(s[q2][kb][s2 * 8 + 2], s[q2][kb][s2 * 8 + 3]);
;           pk.z = pack2(s[q2][kb][s2 * 8 + 4], s[q2][kb][s2 * 8 + 5]);
;           pk.w = pack2(s[q2][kb][s2 * 8 + 6], s[q2][kb][s2 * 8 + 7]);
;           pf[q2] = __builtin_bit_cast(bf8, pk);
;         }
; #pragma unroll
;         for (int d = 0; d < 2; ++d) {
;           const char* vrow = Vs + (d * 32 + r) * 128 + 8 * h;
;           u32x4 vv;
;           const u32x2 lo = *(const u32x2*)(vrow + (((2 * kk) ^ sw) << 4));
;           const u32x2 hi = *(const u32x2*)(vrow + (((2 * kk + 1) ^ sw) << 4));
;           vv.x = lo.x; vv.y = lo.y; vv.z = hi.x; vv.w = hi.y;
;           const bf8 vf = __builtin_bit_cast(bf8, vv);
; #pragma unroll
;           for (int q2 = 0; q2 < 2; ++q2) O[q2][d] = mfma32(vf, pf[q2], O[q2][d]);
;         }
;       }
;     asm volatile("s_waitcnt vmcnt(0)" ::: "memory");
;     __syncthreads();
;     if (tt + 2 < nt) ATTN2_ISSUE(tt + 2, tt & 1)
	v_add_u32_e32 v172, v129, v183
	v_cvt_pk_bf16_f32 v192, v98, v99
	v_cvt_pk_bf16_f32 v193, v100, v101
	v_cvt_pk_bf16_f32 v194, v102, v103
	v_cvt_pk_bf16_f32 v195, v104, v105
	v_cvt_pk_bf16_f32 v218, v66, v67
	v_cvt_pk_bf16_f32 v219, v68, v69
	v_cvt_pk_bf16_f32 v220, v70, v71
	v_cvt_pk_bf16_f32 v221, v72, v73
	ds_read_b64 v[238:239], v172 offset:16384
	ds_read_b64 v[222:223], v172 offset:20480
	v_add_u32_e32 v172, v129, v184
	v_mfma_f32_32x32x16_bf16 v[34:49], v[226:229], v[192:195], v[34:49]
	v_exp_f32_e32 v106, v106
	v_exp_f32_e32 v107, v107
	v_exp_f32_e32 v108, v108
	v_exp_f32_e32 v109, v109
	v_exp_f32_e32 v110, v110
	v_exp_f32_e32 v111, v111
	v_exp_f32_e32 v112, v112
	v_mfma_f32_32x32x16_bf16 v[2:17], v[226:229], v[218:221], v[2:17]
	ds_read_b64 v[240:241], v172 offset:16384
	ds_read_b64 v[224:225], v172 offset:20480
	v_exp_f32_e32 v113, v113
	v_exp_f32_e32 v74, v74
	v_exp_f32_e32 v75, v75
	v_exp_f32_e32 v76, v76
	v_exp_f32_e32 v77, v77
	v_exp_f32_e32 v78, v78
	v_exp_f32_e32 v79, v79
	v_exp_f32_e32 v80, v80
	v_exp_f32_e32 v81, v81
	v_mfma_f32_32x32x16_bf16 v[50:65], v[230:233], v[192:195], v[50:65]
	v_add_u32_e32 v172, v129, v185
	v_cvt_pk_bf16_f32 v192, v106, v107
	v_cvt_pk_bf16_f32 v193, v108, v109
	v_cvt_pk_bf16_f32 v194, v110, v111
	v_cvt_pk_bf16_f32 v195, v112, v113
	v_exp_f32_e32 v114, v114
	v_exp_f32_e32 v115, v115
	v_mfma_f32_32x32x16_bf16 v[18:33], v[230:233], v[218:221], v[18:33]
	s_waitcnt lgkmcnt(0)
	v_cvt_pk_bf16_f32 v218, v74, v75
	v_cvt_pk_bf16_f32 v219, v76, v77
	v_cvt_pk_bf16_f32 v220, v78, v79
	v_cvt_pk_bf16_f32 v221, v80, v81
	ds_read_b64 v[230:231], v172 offset:16384
	ds_read_b64 v[226:227], v172 offset:20480
	v_add_u32_e32 v172, v129, v186
	v_mfma_f32_32x32x16_bf16 v[34:49], v[222:225], v[192:195], v[34:49]
	v_exp_f32_e32 v116, v116
	v_exp_f32_e32 v117, v117
	v_exp_f32_e32 v118, v118
	v_exp_f32_e32 v119, v119
	v_exp_f32_e32 v120, v120
	v_exp_f32_e32 v121, v121
	v_exp_f32_e32 v82, v82
	v_mfma_f32_32x32x16_bf16 v[2:17], v[222:225], v[218:221], v[2:17]
	ds_read_b64 v[232:233], v172 offset:16384
	ds_read_b64 v[228:229], v172 offset:20480
	v_exp_f32_e32 v83, v83
	v_exp_f32_e32 v84, v84
	v_exp_f32_e32 v85, v85
	v_exp_f32_e32 v86, v86
	v_exp_f32_e32 v87, v87
	v_exp_f32_e32 v88, v88
	v_mfma_f32_32x32x16_bf16 v[50:65], v[238:241], v[192:195], v[50:65]
	v_exp_f32_e32 v89, v89
	v_cvt_pk_bf16_f32 v192, v114, v115
	v_cvt_pk_bf16_f32 v193, v116, v117
	v_cvt_pk_bf16_f32 v194, v118, v119
	v_cvt_pk_bf16_f32 v195, v120, v121
	v_add_u32_e32 v172, v129, v187
	v_add_u32_e32 v129, v129, v188
	v_mfma_f32_32x32x16_bf16 v[18:33], v[238:241], v[218:221], v[18:33]
	s_waitcnt lgkmcnt(0)
	v_cvt_pk_bf16_f32 v218, v82, v83
	v_cvt_pk_bf16_f32 v219, v84, v85
	v_cvt_pk_bf16_f32 v220, v86, v87
	v_cvt_pk_bf16_f32 v221, v88, v89
	v_mfma_f32_32x32x16_bf16 v[34:49], v[226:229], v[192:195], v[34:49]
	ds_read_b64 v[238:239], v172 offset:16384
	ds_read_b64 v[222:223], v172 offset:20480
	v_exp_f32_e32 v122, v122
	v_exp_f32_e32 v123, v123
	v_exp_f32_e32 v124, v124
	v_exp_f32_e32 v125, v125
	v_exp_f32_e32 v126, v126
	v_exp_f32_e32 v127, v127
	v_mfma_f32_32x32x16_bf16 v[2:17], v[226:229], v[218:221], v[2:17]
	ds_read_b64 v[240:241], v129 offset:16384
	ds_read_b64 v[224:225], v129 offset:20480
	v_exp_f32_e32 v90, v90
	v_exp_f32_e32 v91, v91
	v_exp_f32_e32 v92, v92
	v_exp_f32_e32 v93, v93
	v_exp_f32_e32 v94, v94
	v_exp_f32_e32 v95, v95
	v_mfma_f32_32x32x16_bf16 v[50:65], v[230:233], v[192:195], v[50:65]
	v_exp_f32_e32 v96, v96
	v_exp_f32_e32 v97, v97
	v_cvt_pk_bf16_f32 v192, v122, v123
	v_cvt_pk_bf16_f32 v193, v124, v125
	v_cvt_pk_bf16_f32 v194, v126, v127
	v_cvt_pk_bf16_f32 v195, v0, v128
	s_waitcnt vmcnt(0)
	v_mfma_f32_32x32x16_bf16 v[18:33], v[230:233], v[218:221], v[18:33]
	s_waitcnt lgkmcnt(0)
	s_waitcnt lgkmcnt(0)
	v_cvt_pk_bf16_f32 v218, v90, v91
	v_cvt_pk_bf16_f32 v219, v92, v93
	v_cvt_pk_bf16_f32 v220, v94, v95
	v_cvt_pk_bf16_f32 v221, v96, v97
	v_mfma_f32_32x32x16_bf16 v[50:65], v[238:241], v[192:195], v[50:65]
	s_cmp_gt_u32 s13, 33
	s_barrier
	v_mfma_f32_32x32x16_bf16 v[18:33], v[238:241], v[218:221], v[18:33]
	v_mfma_f32_32x32x16_bf16 v[34:49], v[222:225], v[192:195], v[34:49]
	v_mfma_f32_32x32x16_bf16 v[2:17], v[222:225], v[218:221], v[2:17]
	s_cbranch_scc1 .LBB0_422
	s_add_i32 s15, s14, s12
	s_add_i32 s14, s14, s0
	v_lshl_add_u64 v[192:193], v[170:171], 0, s[2:3]
	s_mov_b32 m0, s14
	s_nop 0
	global_load_lds_dwordx4 v[192:193], off
	s_mov_b32 m0, s15
	s_nop 0
	global_load_lds_dwordx4 v[168:169], off
	s_branch .LBB0_422

; #define LAS __attribute__((address_space(3)))
; __global__ void __launch_bounds__(512, 2) fwd_megakernel(Params p, int ph_lo, int ph_hi) {
;   __shared__ __attribute__((aligned(16))) char smem[SMEM_BYTES];
;   __shared__ __attribute__((aligned(16))) unsigned xb_words[4];
;   cg::grid_group grid = cg::this_grid();
;   if (threadIdx.x < 4) xb_words[threadIdx.x] = 0u;
;   __syncthreads();
;   const XcdBarrier xb = xcd_barrier_post((unsigned*)(p.ws + OFF_BAR), (volatile LAS unsigned*)xb_words);
	.amdhsa_kernel _Z14fwd_megakernel6Paramsii
		.amdhsa_group_segment_fixed_size 135184
		.amdhsa_private_segment_fixed_size 0
		.amdhsa_kernarg_size 440
		.amdhsa_user_sgpr_count 2
		.amdhsa_user_sgpr_dispatch_ptr 0
		.amdhsa_user_sgpr_queue_ptr 0
		.amdhsa_user_sgpr_kernarg_segment_ptr 1
		.amdhsa_user_sgpr_dispatch_id 0
		.amdhsa_user_sgpr_kernarg_preload_length 0
		.amdhsa_user_sgpr_kernarg_preload_offset 0
		.amdhsa_user_sgpr_private_segment_size 0
		.amdhsa_uses_dynamic_stack 0
		.amdhsa_enable_private_segment 0
		.amdhsa_system_sgpr_workgroup_id_x 1
		.amdhsa_system_sgpr_workgroup_id_y 0
		.amdhsa_system_sgpr_workgroup_id_z 0
		.amdhsa_system_sgpr_workgroup_info 0
		.amdhsa_system_vgpr_workitem_id 2
		.amdhsa_next_free_vgpr 248
		.amdhsa_next_free_sgpr 102
		.amdhsa_accum_offset 248
		.amdhsa_reserve_vcc 1
		.amdhsa_float_round_mode_32 0
		.amdhsa_float_round_mode_16_64 0
		.amdhsa_float_denorm_mode_32 3
		.amdhsa_float_denorm_mode_16_64 3
		.amdhsa_dx10_clamp 1
		.amdhsa_ieee_mode 1
		.amdhsa_fp16_overflow 0
		.amdhsa_tg_split 0
		.amdhsa_exception_fp_ieee_invalid_op 0
		.amdhsa_exception_fp_denorm_src 0
		.amdhsa_exception_fp_ieee_div_zero 0
		.amdhsa_exception_fp_ieee_overflow 0
		.amdhsa_exception_fp_ieee_underflow 0
		.amdhsa_exception_fp_ieee_inexact 0
		.amdhsa_exception_int_div_zero 0
	.end_amdhsa_kernel

; #define LAS __attribute__((address_space(3)))
; __global__ void __launch_bounds__(512, 2) fwd_megakernel(Params p, int ph_lo, int ph_hi) {
;   __shared__ __attribute__((aligned(16))) char smem[SMEM_BYTES];
;   __shared__ __attribute__((aligned(16))) unsigned xb_words[4];
;   cg::grid_group grid = cg::this_grid();
;   if (threadIdx.x < 4) xb_words[threadIdx.x] = 0u;
;   __syncthreads();
;   const XcdBarrier xb = xcd_barrier_post((unsigned*)(p.ws + OFF_BAR), (volatile LAS unsigned*)xb_words);
amdhsa.kernels:
  - .agpr_count:     0
    .args:
      - .offset:         0
        .size:           176
        .value_kind:     by_value
      - .offset:         176
        .size:           4
        .value_kind:     by_value
      - .offset:         180
        .size:           4
        .value_kind:     by_value
      - .offset:         184
        .size:           4
        .value_kind:     hidden_block_count_x
      - .offset:         188
        .size:           4
        .value_kind:     hidden_block_count_y
      - .offset:         192
        .size:           4
        .value_kind:     hidden_block_count_z
      - .offset:         196
        .size:           2
        .value_kind:     hidden_group_size_x
      - .offset:         198
        .size:           2
        .value_kind:     hidden_group_size_y
      - .offset:         200
        .size:           2
        .value_kind:     hidden_group_size_z
      - .offset:         202
        .size:           2
        .value_kind:     hidden_remainder_x
      - .offset:         204
        .size:           2
        .value_kind:     hidden_remainder_y
      - .offset:         206
        .size:           2
        .value_kind:     hidden_remainder_z
      - .offset:         224
        .size:           8
        .value_kind:     hidden_global_offset_x
      - .offset:         232
        .size:           8
        .value_kind:     hidden_global_offset_y
      - .offset:         240
        .size:           8
        .value_kind:     hidden_global_offset_z
      - .offset:         248
        .size:           2
        .value_kind:     hidden_grid_dims
      - .offset:         272
        .size:           8
        .value_kind:     hidden_multigrid_sync_arg
    .group_segment_fixed_size: 135184
    .kernarg_segment_align: 8
    .kernarg_segment_size: 440
    .language:       OpenCL C
    .language_version:
      - 2
      - 0
    .max_flat_workgroup_size: 512
    .name:           _Z14fwd_megakernel6Paramsii
    .private_segment_fixed_size: 0
    .sgpr_count:     108
    .sgpr_spill_count: 179
    .symbol:         _Z14fwd_megakernel6Paramsii.kd
    .uniform_work_group_size: 1
    .uses_dynamic_stack: false
    .vgpr_count:     248
    .vgpr_spill_count: 0
    .wavefront_size: 64
